# v58 + static s_setprio 1 for waves 0-3 (the leading half) per unit K-loop, per-segment flips deleted (mirror of v61)
# baseline (speedup 1.0000x reference)
; template <class Epi, class Sched, bool ALIGN_EPI = false, bool SP2 = false>
; __device__ __forceinline__ void gemm_phase(PG8_LAS unsigned char* lds, const Gemm g, const Sched& S, const Epi& E, const int tid_in) {
;     ...
;         const bool has_next = S.next(ui + 1, nxt);
;         const char* nA = has_next ? (const char*)g.A + (size_t)nxt.pm * tstep : cA; const char* nB = has_next ? (const char*)g.Bt + (size_t)nxt.pn * tstep : cB;
;         for (int t = 0; t < nt; t += 2) {
;             if constexpr (Epi::KSPLIT > 0) { if (t == Epi::KSPLIT / BK) E.midk(acc, cur, wr, wc, fr, fq); }
;             const bool last = (t == nt - 2);
;             const char* a1 = cA + (size_t)(t + 1) * kstep;
;             const char* a2 = last ? nA : cA + (size_t)(t + 2) * kstep; const char* b2 = last ? nB : cB + (size_t)(t + 2) * kstep;
.LBB0_351:
	s_ashr_i32 s27, s26, 31
	s_lshl_b64 s[28:29], s[26:27], 20
	s_add_u32 s28, s1, s28
	s_addc_u32 s29, s5, s29
	s_and_b64 s[30:31], s[36:37], exec
	s_cselect_b32 s27, s29, s35
	s_cselect_b32 s53, s28, s34
	s_ashr_i32 s25, s24, 31
	s_lshl_b64 s[30:31], s[24:25], 20
	s_add_u32 s30, s8, s30
	s_addc_u32 s31, s10, s31
	s_and_b64 s[42:43], s[36:37], exec
	s_cselect_b32 s25, s31, s39
	s_cselect_b32 s54, s30, s38
	s_add_u32 s34, s34, 0x80080
	s_addc_u32 s35, s35, 0
	s_add_u32 s55, s38, 0x100
	v_mov_b32_e32 v0, 0
	s_addc_u32 s56, s39, 0
	s_mov_b32 s57, -2
	s_cmp_lt_u32 s19, 0x1000
	s_cbranch_scc0 .LPRIO_352
	s_setprio 1

; template <class Epi, class Sched, bool ALIGN_EPI = false, bool SP2 = false>
; __device__ __forceinline__ void gemm_phase(PG8_LAS unsigned char* lds, const Gemm g, const Sched& S, const Epi& E, const int tid_in) {
;     ...
;         const bool has_next = S.next(ui + 1, nxt);
;         const char* nA = has_next ? (const char*)g.A + (size_t)nxt.pm * tstep : cA; const char* nB = has_next ? (const char*)g.Bt + (size_t)nxt.pn * tstep : cB;
;         for (int t = 0; t < nt; t += 2) {
;             if constexpr (Epi::KSPLIT > 0) { if (t == Epi::KSPLIT / BK) E.midk(acc, cur, wr, wc, fr, fq); }
;             const bool last = (t == nt - 2);
;             const char* a1 = cA + (size_t)(t + 1) * kstep;
;             const char* a2 = last ? nA : cA + (size_t)(t + 2) * kstep; const char* b2 = last ? nB : cB + (size_t)(t + 2) * kstep;
.LBB0_373:
	s_ashr_i32 s25, s24, 31
	s_lshl_b64 s[26:27], s[24:25], 20
	s_add_u32 s26, s1, s26
	s_addc_u32 s27, s5, s27
	s_and_b64 s[28:29], s[36:37], exec
	s_cselect_b32 s21, s27, s35
	s_cselect_b32 s25, s26, s34
	s_ashr_i32 s23, s22, 31
	s_lshl_b64 s[28:29], s[22:23], 20
	s_add_u32 s28, s8, s28
	s_addc_u32 s29, s10, s29
	s_and_b64 s[42:43], s[36:37], exec
	s_cselect_b32 s23, s29, s39
	s_cselect_b32 s51, s28, s38
	s_add_u32 s34, s34, 0x80080
	s_addc_u32 s35, s35, 0
	s_add_u32 s52, s38, 0x100
	v_mov_b32_e32 v0, 0
	s_addc_u32 s53, s39, 0
	s_mov_b32 s54, -2
	s_cmp_lt_u32 s19, 0x1000
	s_cbranch_scc0 .LPRIO_374
	s_setprio 1

; template <class Epi, class Sched, bool ALIGN_EPI = false, bool SP2 = false>
; __device__ __forceinline__ void gemm_phase(PG8_LAS unsigned char* lds, const Gemm g, const Sched& S, const Epi& E, const int tid_in) {
;     ...
;         const bool has_next = S.next(ui + 1, nxt);
;         const char* nA = has_next ? (const char*)g.A + (size_t)nxt.pm * tstep : cA; const char* nB = has_next ? (const char*)g.Bt + (size_t)nxt.pn * tstep : cB;
;         for (int t = 0; t < nt; t += 2) {
;             if constexpr (Epi::KSPLIT > 0) { if (t == Epi::KSPLIT / BK) E.midk(acc, cur, wr, wc, fr, fq); }
;             const bool last = (t == nt - 2);
;             const char* a1 = cA + (size_t)(t + 1) * kstep;
;             const char* a2 = last ? nA : cA + (size_t)(t + 2) * kstep; const char* b2 = last ? nB : cB + (size_t)(t + 2) * kstep;
.LBB0_393:
	s_ashr_i32 s23, s22, 31
	s_lshl_b64 s[24:25], s[22:23], 20
	s_add_u32 s24, s1, s24
	s_addc_u32 s25, s5, s25
	s_and_b64 s[26:27], s[36:37], exec
	s_cselect_b32 s23, s25, s29
	s_cselect_b32 s49, s24, s28
	s_ashr_i32 s21, s20, 31
	s_lshl_b64 s[26:27], s[20:21], 20
	s_add_u32 s26, s8, s26
	s_addc_u32 s27, s10, s27
	s_and_b64 s[34:35], s[36:37], exec
	s_cselect_b32 s21, s27, s31
	s_cselect_b32 s50, s26, s30
	s_add_u32 s28, s28, 0x80080
	s_addc_u32 s29, s29, 0
	s_add_u32 s51, s30, 0x100
	v_mov_b32_e32 v0, 0
	s_addc_u32 s52, s31, 0
	s_mov_b32 s53, -2
	s_cmp_lt_u32 s19, 0x1000
	s_cbranch_scc0 .LPRIO_394
	s_setprio 1

; template <class Epi, class Sched, bool ALIGN_EPI = false, bool SP2 = false>
; __device__ __forceinline__ void gemm_phase(PG8_LAS unsigned char* lds, const Gemm g, const Sched& S, const Epi& E, const int tid_in) {
;     ...
;         const bool has_next = S.next(ui + 1, nxt);
;         const char* nA = has_next ? (const char*)g.A + (size_t)nxt.pm * tstep : cA; const char* nB = has_next ? (const char*)g.Bt + (size_t)nxt.pn * tstep : cB;
;         for (int t = 0; t < nt; t += 2) {
;             if constexpr (Epi::KSPLIT > 0) { if (t == Epi::KSPLIT / BK) E.midk(acc, cur, wr, wc, fr, fq); }
;             const bool last = (t == nt - 2);
;             const char* a1 = cA + (size_t)(t + 1) * kstep;
;             const char* a2 = last ? nA : cA + (size_t)(t + 2) * kstep; const char* b2 = last ? nB : cB + (size_t)(t + 2) * kstep;
.LBB0_411:
	s_ashr_i32 s27, s26, 31
	s_lshl_b64 s[28:29], s[26:27], 20
	s_add_u32 s28, s1, s28
	s_addc_u32 s29, s5, s29
	s_and_b64 s[30:31], s[36:37], exec
	s_cselect_b32 s27, s29, s35
	s_cselect_b32 s54, s28, s34
	s_ashr_i32 s7, s6, 31
	s_lshl_b64 s[30:31], s[6:7], 20
	s_add_u32 s30, s8, s30
	s_addc_u32 s31, s10, s31
	s_and_b64 s[42:43], s[36:37], exec
	s_cselect_b32 s7, s31, s39
	s_cselect_b32 s55, s30, s38
	s_add_u32 s34, s34, 0x80080
	s_addc_u32 s35, s35, 0
	s_add_u32 s56, s38, 0x100
	v_mov_b32_e32 v0, 0
	s_addc_u32 s57, s39, 0
	s_mov_b32 s58, -2
	s_cmp_lt_u32 s19, 0x1000
	s_cbranch_scc0 .LPRIO_412
	s_setprio 1

; template <class Epi, class Sched, bool ALIGN_EPI = false, bool SP2 = false>
; __device__ __forceinline__ void gemm_phase(PG8_LAS unsigned char* lds, const Gemm g, const Sched& S, const Epi& E, const int tid_in) {
;     ...
;         const bool has_next = S.next(ui + 1, nxt);
;         const char* nA = has_next ? (const char*)g.A + (size_t)nxt.pm * tstep : cA; const char* nB = has_next ? (const char*)g.Bt + (size_t)nxt.pn * tstep : cB;
;         for (int t = 0; t < nt; t += 2) {
;     ...
; #pragma unroll
;         for (int a = 0; a < 2; ++a)
; #pragma unroll
;             for (int b = 0; b < 2; ++b)
; #pragma unroll
;                 for (int m = 0; m < 4; ++m)
; #pragma unroll
;                     for (int n = 0; n < 2; ++n) acc[a][b][m][n] = (f32x4){0.f, 0.f, 0.f, 0.f};
;         cur = nxt; cA = nA; cB = nB; ++ui;
.LBB0_959:
	s_lshl_b32 s54, s36, 8
	s_lshl_b32 s55, s53, 9
	s_add_i32 s56, s54, s46
	s_add_i32 s57, s49, s55
	s_add_u32 s36, s30, 0x60080
	s_addc_u32 s37, s31, 0
	s_add_u32 s58, s34, 0x100
	v_mov_b32_e32 v0, 0
	v_lshl_add_u64 v[182:183], s[36:37], 0, v[202:203]
	v_lshl_add_u64 v[184:185], s[36:37], 0, v[204:205]
	s_addc_u32 s59, s35, 0
	s_mov_b32 s60, -2
	s_mov_b64 s[34:35], 0
	v_mov_b32_e32 v1, v0
	v_mov_b32_e32 v2, v0
	v_mov_b32_e32 v3, v0
	v_mov_b32_e32 v4, v0
	v_mov_b32_e32 v5, v0
	v_mov_b32_e32 v6, v0
	v_mov_b32_e32 v7, v0
	v_mov_b32_e32 v8, v0
	v_mov_b32_e32 v9, v0
	v_mov_b32_e32 v10, v0
	v_mov_b32_e32 v11, v0
	v_mov_b32_e32 v16, v0
	v_mov_b32_e32 v17, v0
	v_mov_b32_e32 v18, v0
	v_mov_b32_e32 v19, v0
	v_mov_b32_e32 v26, v0
	v_mov_b32_e32 v27, v0
	v_mov_b32_e32 v28, v0
	v_mov_b32_e32 v29, v0
	v_mov_b32_e32 v34, v0
	v_mov_b32_e32 v35, v0
	v_mov_b32_e32 v36, v0
	v_mov_b32_e32 v37, v0
	v_mov_b32_e32 v42, v0
	v_mov_b32_e32 v43, v0
	v_mov_b32_e32 v44, v0
	v_mov_b32_e32 v45, v0
	v_mov_b32_e32 v50, v0
	v_mov_b32_e32 v51, v0
	v_mov_b32_e32 v52, v0
	v_mov_b32_e32 v53, v0
	v_mov_b32_e32 v12, v0
	v_mov_b32_e32 v13, v0
	v_mov_b32_e32 v14, v0
	v_mov_b32_e32 v15, v0
	v_mov_b32_e32 v22, v0
	v_mov_b32_e32 v23, v0
	v_mov_b32_e32 v24, v0
	v_mov_b32_e32 v25, v0
	v_mov_b32_e32 v30, v0
	v_mov_b32_e32 v31, v0
	v_mov_b32_e32 v32, v0
	v_mov_b32_e32 v33, v0
	v_mov_b32_e32 v38, v0
	v_mov_b32_e32 v39, v0
	v_mov_b32_e32 v40, v0
	v_mov_b32_e32 v41, v0
	v_mov_b32_e32 v46, v0
	v_mov_b32_e32 v47, v0
	v_mov_b32_e32 v48, v0
	v_mov_b32_e32 v49, v0
	v_mov_b32_e32 v54, v0
	v_mov_b32_e32 v55, v0
	v_mov_b32_e32 v56, v0
	v_mov_b32_e32 v57, v0
	v_mov_b32_e32 v58, v0
	v_mov_b32_e32 v59, v0
	v_mov_b32_e32 v60, v0
	v_mov_b32_e32 v61, v0
	v_mov_b32_e32 v62, v0
	v_mov_b32_e32 v63, v0
	v_mov_b32_e32 v64, v0
	v_mov_b32_e32 v65, v0
	v_mov_b32_e32 v66, v0
	v_mov_b32_e32 v67, v0
	v_mov_b32_e32 v68, v0
	v_mov_b32_e32 v69, v0
	v_mov_b32_e32 v70, v0
	v_mov_b32_e32 v71, v0
	v_mov_b32_e32 v72, v0
	v_mov_b32_e32 v73, v0
	v_mov_b32_e32 v74, v0
	v_mov_b32_e32 v75, v0
	v_mov_b32_e32 v76, v0
	v_mov_b32_e32 v77, v0
	v_mov_b32_e32 v82, v0
	v_mov_b32_e32 v83, v0
	v_mov_b32_e32 v84, v0
	v_mov_b32_e32 v85, v0
	v_mov_b32_e32 v90, v0
	v_mov_b32_e32 v91, v0
	v_mov_b32_e32 v92, v0
	v_mov_b32_e32 v93, v0
	v_mov_b32_e32 v98, v0
	v_mov_b32_e32 v99, v0
	v_mov_b32_e32 v100, v0
	v_mov_b32_e32 v101, v0
	v_mov_b32_e32 v114, v0
	v_mov_b32_e32 v115, v0
	v_mov_b32_e32 v116, v0
	v_mov_b32_e32 v117, v0
	v_mov_b32_e32 v118, v0
	v_mov_b32_e32 v119, v0
	v_mov_b32_e32 v120, v0
	v_mov_b32_e32 v121, v0
	v_mov_b32_e32 v78, v0
	v_mov_b32_e32 v79, v0
	v_mov_b32_e32 v80, v0
	v_mov_b32_e32 v81, v0
	v_mov_b32_e32 v86, v0
	v_mov_b32_e32 v87, v0
	v_mov_b32_e32 v88, v0
	v_mov_b32_e32 v89, v0
	v_mov_b32_e32 v94, v0
	v_mov_b32_e32 v95, v0
	v_mov_b32_e32 v96, v0
	v_mov_b32_e32 v97, v0
	v_mov_b32_e32 v102, v0
	v_mov_b32_e32 v103, v0
	v_mov_b32_e32 v104, v0
	v_mov_b32_e32 v105, v0
	v_mov_b32_e32 v106, v0
	v_mov_b32_e32 v107, v0
	v_mov_b32_e32 v108, v0
	v_mov_b32_e32 v109, v0
	v_mov_b32_e32 v110, v0
	v_mov_b32_e32 v111, v0
	v_mov_b32_e32 v112, v0
	v_mov_b32_e32 v113, v0
	v_mov_b32_e32 v122, v0
	v_mov_b32_e32 v123, v0
	v_mov_b32_e32 v124, v0
	v_mov_b32_e32 v125, v0
	v_mov_b32_e32 v126, v0
	v_mov_b32_e32 v127, v0
	v_mov_b32_e32 v128, v0
	v_mov_b32_e32 v129, v0
	s_cmp_lt_u32 s19, 0x1000
	s_cbranch_scc0 .LPRIO_960
	s_setprio 1

; template <class Epi, class Sched, bool ALIGN_EPI = false, bool SP2 = false>
; __device__ __forceinline__ void gemm_phase(PG8_LAS unsigned char* lds, const Gemm g, const Sched& S, const Epi& E, const int tid_in) {
;     ...
;         const bool has_next = S.next(ui + 1, nxt);
;         const char* nA = has_next ? (const char*)g.A + (size_t)nxt.pm * tstep : cA; const char* nB = has_next ? (const char*)g.Bt + (size_t)nxt.pn * tstep : cB;
;         for (int t = 0; t < nt; t += 2) {
;             if constexpr (Epi::KSPLIT > 0) { if (t == Epi::KSPLIT / BK) E.midk(acc, cur, wr, wc, fr, fq); }
;             const bool last = (t == nt - 2);
;             const char* a1 = cA + (size_t)(t + 1) * kstep;
;             const char* a2 = last ? nA : cA + (size_t)(t + 2) * kstep; const char* b2 = last ? nB : cB + (size_t)(t + 2) * kstep;
.LBB0_1036:
	s_ashr_i32 s57, s56, 31
	s_lshl_b64 s[34:35], s[56:57], 20
	s_add_u32 s36, s10, s34
	s_addc_u32 s37, s19, s35
	s_and_b64 s[34:35], exec, s[6:7]
	v_readlane_b32 s34, v254, 36
	v_readlane_b32 s35, v254, 37
	s_cselect_b32 s38, s29, s37
	s_cselect_b32 s39, s28, s36
	s_mov_b32 s40, s34
	s_ashr_i32 s41, s34, 31
	v_writelane_b32 v254, s34, 36
	v_mov_b32_e32 v0, 0
	s_mov_b32 vcc_lo, -2
	v_writelane_b32 v254, s35, 37
	s_lshl_b64 s[34:35], s[40:41], 20
	s_add_u32 s60, s62, s34
	s_addc_u32 s61, s63, s35
	s_and_b64 s[34:35], exec, s[6:7]
	s_cselect_b32 s40, s31, s61
	s_cselect_b32 s41, s30, s60
	s_add_u32 s28, s28, 0x80080
	s_addc_u32 s29, s29, 0
	s_add_u32 s57, s30, 0x100
	s_addc_u32 s92, s31, 0
	s_cmp_lt_u32 s8, 0x1000
	s_cbranch_scc0 .LPRIO_1037
	s_setprio 1

; template <class Epi, class Sched, bool ALIGN_EPI = false, bool SP2 = false>
; __device__ __forceinline__ void gemm_phase(PG8_LAS unsigned char* lds, const Gemm g, const Sched& S, const Epi& E, const int tid_in) {
;     ...
;         const bool has_next = S.next(ui + 1, nxt);
;         const char* nA = has_next ? (const char*)g.A + (size_t)nxt.pm * tstep : cA; const char* nB = has_next ? (const char*)g.Bt + (size_t)nxt.pn * tstep : cB;
;         for (int t = 0; t < nt; t += 2) {
;             if constexpr (Epi::KSPLIT > 0) { if (t == Epi::KSPLIT / BK) E.midk(acc, cur, wr, wc, fr, fq); }
;             const bool last = (t == nt - 2);
;             const char* a1 = cA + (size_t)(t + 1) * kstep;
;             const char* a2 = last ? nA : cA + (size_t)(t + 2) * kstep; const char* b2 = last ? nB : cB + (size_t)(t + 2) * kstep;
.LBB0_1156:
	s_ashr_i32 s35, s34, 31
	s_lshl_b64 s[6:7], s[34:35], 20
	s_add_u32 s6, s5, s6
	s_addc_u32 s7, s8, s7
	s_and_b64 s[20:21], exec, s[48:49]
	s_cselect_b32 s35, s51, s7
	s_cselect_b32 s58, s50, s6
	s_ashr_i32 s31, s30, 31
	s_lshl_b64 s[20:21], s[30:31], 20
	s_add_u32 s20, s10, s20
	s_addc_u32 s21, s19, s21
	s_and_b64 s[54:55], exec, s[48:49]
	s_cselect_b32 s31, s53, s21
	s_cselect_b32 s59, s52, s20
	s_add_u32 s50, s50, 0x80080
	s_addc_u32 s51, s51, 0
	s_add_u32 s60, s52, 0x100
	v_mov_b32_e32 v0, 0
	s_addc_u32 s61, s53, 0
	s_mov_b32 s62, -2
	s_cmp_lt_u32 s1, 0x1000
	s_cbranch_scc0 .LPRIO_1157
	s_setprio 1

; template <class Epi, class Sched, bool ALIGN_EPI = false, bool SP2 = false>
; __device__ __forceinline__ void gemm_phase(PG8_LAS unsigned char* lds, const Gemm g, const Sched& S, const Epi& E, const int tid_in) {
;     ...
;         const bool has_next = S.next(ui + 1, nxt);
;         const char* nA = has_next ? (const char*)g.A + (size_t)nxt.pm * tstep : cA; const char* nB = has_next ? (const char*)g.Bt + (size_t)nxt.pn * tstep : cB;
;         for (int t = 0; t < nt; t += 2) {
;             if constexpr (Epi::KSPLIT > 0) { if (t == Epi::KSPLIT / BK) E.midk(acc, cur, wr, wc, fr, fq); }
;             const bool last = (t == nt - 2);
;             const char* a1 = cA + (size_t)(t + 1) * kstep;
;             const char* a2 = last ? nA : cA + (size_t)(t + 2) * kstep; const char* b2 = last ? nB : cB + (size_t)(t + 2) * kstep;
.LBB0_1304:
	s_add_u32 s54, s30, 0x100
	v_mov_b32_e32 v0, 0
	s_addc_u32 s55, s31, 0
	s_mov_b32 s56, -2
	s_cmp_lt_u32 s19, 0x1000
	s_cbranch_scc0 .LPRIO_1305
	s_setprio 1
